# stack: 5th-round attention units moved off the chunk-0 GLA blocks; norm phases' 9th-row tail dealt one row per block; hand-written norm0 (3 rows/iter); on top of v17
# speedup vs baseline: 1.0173x; 1.0049x over previous
.LBB0_623:
	s_add_i32 s13, s12, s2
	s_cmp_lg_u32 s96, 0x100
	s_cbranch_scc1 .Lp2_no5
	s_cmpk_lg_i32 s12, 0x400
	s_cbranch_scc1 .Lp2_no5
	s_add_i32 s13, s13, -16
	s_cmp_lt_u32 s2, 16
	s_cselect_b32 s13, 0x7ff, s13
.Lp2_no5:
	s_mov_b32 s20, s12
	s_cmpk_gt_i32 s20, 0x40f
	s_mov_b32 s20, 2
	s_cbranch_scc1 .LBB0_698

.LnrmA_loop:
	s_mov_b32 s37, s36
	s_cmpk_gt_i32 s37, 0x207f
	s_cselect_b32 s43, 0x2080, 0
	s_cselect_b32 vcc_lo, 0x2000, 0
	s_cselect_b32 vcc_hi, 0x80, 0
	s_sub_i32 s43, s37, s43
	s_add_i32 vcc_lo, vcc_lo, s43
	s_addk_i32 vcc_lo, 0xff80
	s_add_i32 vcc_hi, vcc_hi, s43
	s_cmpk_lt_i32 s43, 0x80
	s_cselect_b32 vcc_lo, vcc_hi, vcc_lo
	s_cselect_b32 s0, s40, s92
	s_cselect_b32 s1, s41, s93
	s_lshl_b32 vcc_lo, vcc_lo, 12
	s_lshl_b32 vcc_hi, s37, 11
	v_add_u32_e32 v114, vcc_lo, v106
	v_add_u32_e32 v117, vcc_hi, v107
	global_load_dwordx2 v[16:17], v117, s[4:5] nt
	global_load_dwordx2 v[18:19], v117, s[4:5] offset:512 nt
	global_load_dwordx2 v[20:21], v117, s[4:5] offset:1024 nt
	global_load_dwordx2 v[22:23], v117, s[4:5] offset:1536 nt
	global_load_dwordx4 v[0:3], v114, s[0:1] nt
	global_load_dwordx4 v[4:7], v114, s[0:1] offset:1024 nt
	global_load_dwordx4 v[8:11], v114, s[0:1] offset:2048 nt
	global_load_dwordx4 v[12:15], v114, s[0:1] offset:3072 nt
	s_add_i32 s37, s36, s14
	s_cmpk_lt_i32 s37, 0x4100
	s_cselect_b32 s37, s37, s36
	s_cmpk_gt_i32 s37, 0x207f
	s_cselect_b32 s43, 0x2080, 0
	s_cselect_b32 vcc_lo, 0x2000, 0
	s_cselect_b32 vcc_hi, 0x80, 0
	s_sub_i32 s43, s37, s43
	s_add_i32 vcc_lo, vcc_lo, s43
	s_addk_i32 vcc_lo, 0xff80
	s_add_i32 vcc_hi, vcc_hi, s43
	s_cmpk_lt_i32 s43, 0x80
	s_cselect_b32 vcc_lo, vcc_hi, vcc_lo
	s_cselect_b32 s12, s40, s92
	s_cselect_b32 s13, s41, s93
	s_lshl_b32 vcc_lo, vcc_lo, 12
	s_lshl_b32 vcc_hi, s37, 11
	v_add_u32_e32 v115, vcc_lo, v106
	v_add_u32_e32 v118, vcc_hi, v107
	global_load_dwordx2 v[40:41], v118, s[4:5] nt
	global_load_dwordx2 v[42:43], v118, s[4:5] offset:512 nt
	global_load_dwordx2 v[44:45], v118, s[4:5] offset:1024 nt
	global_load_dwordx2 v[46:47], v118, s[4:5] offset:1536 nt
	global_load_dwordx4 v[24:27], v115, s[12:13] nt
	global_load_dwordx4 v[28:31], v115, s[12:13] offset:1024 nt
	global_load_dwordx4 v[32:35], v115, s[12:13] offset:2048 nt
	global_load_dwordx4 v[36:39], v115, s[12:13] offset:3072 nt
	s_lshl_b32 s37, s14, 1
	s_add_i32 s37, s36, s37
	s_cmpk_lg_i32 s14, 0x800
	s_cbranch_scc1 .Lnrmtail_1
	s_cmpk_lt_i32 s37, 0x4000
	s_cbranch_scc1 .Lnrmtail_1
	s_sub_i32 vcc_lo, s36, s82
	s_and_b32 vcc_lo, vcc_lo, 7
	s_add_i32 s37, s2, 0x4000
	s_cmp_eq_u32 vcc_lo, 0
	s_cselect_b32 s37, s37, 0x7fff
.Lnrmtail_1:
	s_cmpk_lt_i32 s37, 0x4100
	s_cselect_b32 s37, s37, s36
	s_cmpk_gt_i32 s37, 0x207f
	s_cselect_b32 s43, 0x2080, 0
	s_cselect_b32 vcc_lo, 0x2000, 0
	s_cselect_b32 vcc_hi, 0x80, 0
	s_sub_i32 s43, s37, s43
	s_add_i32 vcc_lo, vcc_lo, s43
	s_addk_i32 vcc_lo, 0xff80
	s_add_i32 vcc_hi, vcc_hi, s43
	s_cmpk_lt_i32 s43, 0x80
	s_cselect_b32 vcc_lo, vcc_hi, vcc_lo
	s_cselect_b32 s38, s40, s92
	s_cselect_b32 s39, s41, s93
	s_lshl_b32 vcc_lo, vcc_lo, 12
	s_lshl_b32 vcc_hi, s37, 11
	v_add_u32_e32 v116, vcc_lo, v106
	v_add_u32_e32 v119, vcc_hi, v107
	global_load_dwordx2 v[64:65], v119, s[4:5] nt
	global_load_dwordx2 v[66:67], v119, s[4:5] offset:512 nt
	global_load_dwordx2 v[68:69], v119, s[4:5] offset:1024 nt
	global_load_dwordx2 v[70:71], v119, s[4:5] offset:1536 nt
	global_load_dwordx4 v[48:51], v116, s[38:39] nt
	global_load_dwordx4 v[52:55], v116, s[38:39] offset:1024 nt
	global_load_dwordx4 v[56:59], v116, s[38:39] offset:2048 nt
	global_load_dwordx4 v[60:63], v116, s[38:39] offset:3072 nt
	s_waitcnt vmcnt(16)
	v_lshlrev_b32_e32 v120, 16, v16
	v_and_b32_e32 v16, 0xffff0000, v16
	v_lshlrev_b32_e32 v121, 16, v17
	v_and_b32_e32 v17, 0xffff0000, v17
	v_lshlrev_b32_e32 v122, 16, v18
	v_and_b32_e32 v18, 0xffff0000, v18
	v_lshlrev_b32_e32 v123, 16, v19
	v_and_b32_e32 v19, 0xffff0000, v19
	v_lshlrev_b32_e32 v124, 16, v20
	v_and_b32_e32 v20, 0xffff0000, v20
	v_lshlrev_b32_e32 v125, 16, v21
	v_and_b32_e32 v21, 0xffff0000, v21
	v_lshlrev_b32_e32 v126, 16, v22
	v_and_b32_e32 v22, 0xffff0000, v22
	v_lshlrev_b32_e32 v127, 16, v23
	v_and_b32_e32 v23, 0xffff0000, v23
	v_mul_f32_e32 v128, v16, v16
	v_mul_f32_e32 v129, v18, v18
	v_mul_f32_e32 v130, v20, v20
	v_mul_f32_e32 v131, v22, v22
	v_fmac_f32_e32 v128, v120, v120
	v_fmac_f32_e32 v129, v122, v122
	v_fmac_f32_e32 v130, v124, v124
	v_fmac_f32_e32 v131, v126, v126
	v_fmac_f32_e32 v128, v121, v121
	v_fmac_f32_e32 v129, v123, v123
	v_fmac_f32_e32 v130, v125, v125
	v_fmac_f32_e32 v131, v127, v127
	v_fmac_f32_e32 v128, v17, v17
	v_fmac_f32_e32 v129, v19, v19
	v_fmac_f32_e32 v130, v21, v21
	v_fmac_f32_e32 v131, v23, v23
	v_add_f32_e32 v132, v128, v129
	v_add_f32_e32 v132, v132, v130
	v_add_f32_e32 v132, v132, v131
	ds_bpermute_b32 v138, v108, v132
	s_waitcnt lgkmcnt(0)
	v_add_f32_e32 v132, v132, v138
	ds_bpermute_b32 v138, v109, v132
	s_waitcnt lgkmcnt(0)
	v_add_f32_e32 v132, v132, v138
	ds_bpermute_b32 v138, v110, v132
	s_waitcnt lgkmcnt(0)
	v_add_f32_e32 v132, v132, v138
	ds_bpermute_b32 v138, v111, v132
	s_waitcnt lgkmcnt(0)
	v_add_f32_e32 v132, v132, v138
	ds_bpermute_b32 v138, v112, v132
	s_waitcnt lgkmcnt(0)
	v_add_f32_e32 v132, v132, v138
	ds_bpermute_b32 v138, v113, v132
	s_waitcnt lgkmcnt(0)
	v_add_f32_e32 v132, v132, v138
	v_fmamk_f32 v132, v132, 0x3a800000, v177
	v_mov_b32_e32 v135, 0x800000
	v_cmp_gt_f32_e32 vcc, v135, v132
	v_mul_f32_e32 v133, 0x4b800000, v132
	s_nop 1
	v_cndmask_b32_e32 v132, v132, v133, vcc
	v_rsq_f32_e32 v132, v132
	s_nop 0
	v_mul_f32_e32 v133, 0x45800000, v132
	v_cndmask_b32_e32 v134, v132, v133, vcc
	v_mul_f32_e32 v120, v72, v120
	v_mul_f32_e32 v16, v73, v16
	v_mul_f32_e32 v121, v74, v121
	v_mul_f32_e32 v17, v75, v17
	v_mul_f32_e32 v122, v76, v122
	v_mul_f32_e32 v18, v77, v18
	v_mul_f32_e32 v123, v78, v123
	v_mul_f32_e32 v19, v79, v19
	v_mul_f32_e32 v124, v80, v124
	v_mul_f32_e32 v20, v81, v20
	v_mul_f32_e32 v125, v82, v125
	v_mul_f32_e32 v21, v83, v21
	v_mul_f32_e32 v126, v84, v126
	v_mul_f32_e32 v22, v85, v22
	v_mul_f32_e32 v127, v86, v127
	v_mul_f32_e32 v23, v87, v23
	v_fmac_f32_e32 v0, v120, v134
	v_fmac_f32_e32 v1, v16, v134
	v_fmac_f32_e32 v2, v121, v134
	v_fmac_f32_e32 v3, v17, v134
	v_fmac_f32_e32 v4, v122, v134
	v_fmac_f32_e32 v5, v18, v134
	v_fmac_f32_e32 v6, v123, v134
	v_fmac_f32_e32 v7, v19, v134
	v_fmac_f32_e32 v8, v124, v134
	v_fmac_f32_e32 v9, v20, v134
	v_fmac_f32_e32 v10, v125, v134
	v_fmac_f32_e32 v11, v21, v134
	v_fmac_f32_e32 v12, v126, v134
	v_fmac_f32_e32 v13, v22, v134
	v_fmac_f32_e32 v14, v127, v134
	v_fmac_f32_e32 v15, v23, v134
	global_store_dwordx4 v114, v[0:3], s[0:1] nt
	global_store_dwordx4 v114, v[4:7], s[0:1] offset:1024 nt
	global_store_dwordx4 v114, v[8:11], s[0:1] offset:2048 nt
	global_store_dwordx4 v114, v[12:15], s[0:1] offset:3072 nt
	s_cmp_eq_u32 s42, 0
	s_cbranch_scc1 .LnrmA_nopre0
	v_mul_f32_e32 v128, v1, v1
	v_mul_f32_e32 v129, v5, v5
	v_mul_f32_e32 v130, v9, v9
	v_mul_f32_e32 v131, v13, v13
	v_fmac_f32_e32 v128, v0, v0
	v_fmac_f32_e32 v129, v4, v4
	v_fmac_f32_e32 v130, v8, v8
	v_fmac_f32_e32 v131, v12, v12
	v_fmac_f32_e32 v128, v2, v2
	v_fmac_f32_e32 v129, v6, v6
	v_fmac_f32_e32 v130, v10, v10
	v_fmac_f32_e32 v131, v14, v14
	v_fmac_f32_e32 v128, v3, v3
	v_fmac_f32_e32 v129, v7, v7
	v_fmac_f32_e32 v130, v11, v11
	v_fmac_f32_e32 v131, v15, v15
	v_add_f32_e32 v132, v128, v129
	v_add_f32_e32 v132, v130, v132
	v_add_f32_e32 v132, v131, v132
	ds_bpermute_b32 v138, v108, v132
	s_waitcnt lgkmcnt(0)
	v_add_f32_e32 v132, v132, v138
	ds_bpermute_b32 v138, v109, v132
	s_waitcnt lgkmcnt(0)
	v_add_f32_e32 v132, v132, v138
	ds_bpermute_b32 v138, v110, v132
	s_waitcnt lgkmcnt(0)
	v_add_f32_e32 v132, v132, v138
	ds_bpermute_b32 v138, v111, v132
	s_waitcnt lgkmcnt(0)
	v_add_f32_e32 v132, v132, v138
	ds_bpermute_b32 v138, v112, v132
	s_waitcnt lgkmcnt(0)
	v_add_f32_e32 v132, v132, v138
	ds_bpermute_b32 v138, v113, v132
	s_waitcnt lgkmcnt(0)
	v_add_f32_e32 v132, v132, v138
	v_fmamk_f32 v132, v132, 0x3a800000, v177
	v_mov_b32_e32 v135, 0x800000
	v_cmp_gt_f32_e32 vcc, v135, v132
	v_mul_f32_e32 v133, 0x4b800000, v132
	s_nop 1
	v_cndmask_b32_e32 v132, v132, v133, vcc
	v_rsq_f32_e32 v132, v132
	s_nop 0
	v_mul_f32_e32 v133, 0x45800000, v132
	v_cndmask_b32_e32 v134, v132, v133, vcc
	v_mul_f32_e32 v0, v0, v88
	v_mul_f32_e32 v1, v1, v89
	v_mul_f32_e32 v2, v2, v90
	v_mul_f32_e32 v3, v3, v91
	v_mul_f32_e32 v4, v4, v92
	v_mul_f32_e32 v5, v5, v93
	v_mul_f32_e32 v6, v6, v94
	v_mul_f32_e32 v7, v7, v95
	v_mul_f32_e32 v8, v8, v96
	v_mul_f32_e32 v9, v9, v97
	v_mul_f32_e32 v10, v10, v98
	v_mul_f32_e32 v11, v11, v99
	v_mul_f32_e32 v12, v12, v100
	v_mul_f32_e32 v13, v13, v101
	v_mul_f32_e32 v14, v14, v102
	v_mul_f32_e32 v15, v15, v103
	v_mul_f32_e32 v0, v0, v134
	v_mul_f32_e32 v1, v1, v134
	v_mul_f32_e32 v2, v2, v134
	v_mul_f32_e32 v3, v3, v134
	v_mul_f32_e32 v4, v4, v134
	v_mul_f32_e32 v5, v5, v134
	v_mul_f32_e32 v6, v6, v134
	v_mul_f32_e32 v7, v7, v134
	v_mul_f32_e32 v8, v8, v134
	v_mul_f32_e32 v9, v9, v134
	v_mul_f32_e32 v10, v10, v134
	v_mul_f32_e32 v11, v11, v134
	v_mul_f32_e32 v12, v12, v134
	v_mul_f32_e32 v13, v13, v134
	v_mul_f32_e32 v14, v14, v134
	v_mul_f32_e32 v15, v15, v134
	v_cvt_pk_bf16_f32 v120, v0, v1
	v_cvt_pk_bf16_f32 v121, v2, v3
	v_cvt_pk_bf16_f32 v122, v4, v5
	v_cvt_pk_bf16_f32 v123, v6, v7
	v_cvt_pk_bf16_f32 v124, v8, v9
	v_cvt_pk_bf16_f32 v125, v10, v11
	v_cvt_pk_bf16_f32 v126, v12, v13
	v_cvt_pk_bf16_f32 v127, v14, v15
	global_store_dwordx2 v117, v[120:121], s[4:5] nt
	global_store_dwordx2 v117, v[122:123], s[4:5] offset:512 nt
	global_store_dwordx2 v117, v[124:125], s[4:5] offset:1024 nt
	global_store_dwordx2 v117, v[126:127], s[4:5] offset:1536 nt

.LnrmA_skip1:
	s_lshl_b32 s37, s14, 1
	s_add_i32 s37, s36, s37
	s_cmpk_lg_i32 s14, 0x800
	s_cbranch_scc1 .Lnrmtail_2
	s_cmpk_lt_i32 s37, 0x4000
	s_cbranch_scc1 .Lnrmtail_2
	s_sub_i32 vcc_lo, s36, s82
	s_and_b32 vcc_lo, vcc_lo, 7
	s_add_i32 s37, s2, 0x4000
	s_cmp_eq_u32 vcc_lo, 0
	s_cselect_b32 s37, s37, 0x7fff
.Lnrmtail_2:
	s_cmpk_lt_i32 s37, 0x4100
	s_cbranch_scc0 .LnrmA_skip2
	s_waitcnt vmcnt(8)
	v_lshlrev_b32_e32 v120, 16, v64
	v_and_b32_e32 v64, 0xffff0000, v64
	v_lshlrev_b32_e32 v121, 16, v65
	v_and_b32_e32 v65, 0xffff0000, v65
	v_lshlrev_b32_e32 v122, 16, v66
	v_and_b32_e32 v66, 0xffff0000, v66
	v_lshlrev_b32_e32 v123, 16, v67
	v_and_b32_e32 v67, 0xffff0000, v67
	v_lshlrev_b32_e32 v124, 16, v68
	v_and_b32_e32 v68, 0xffff0000, v68
	v_lshlrev_b32_e32 v125, 16, v69
	v_and_b32_e32 v69, 0xffff0000, v69
	v_lshlrev_b32_e32 v126, 16, v70
	v_and_b32_e32 v70, 0xffff0000, v70
	v_lshlrev_b32_e32 v127, 16, v71
	v_and_b32_e32 v71, 0xffff0000, v71
	v_mul_f32_e32 v128, v64, v64
	v_mul_f32_e32 v129, v66, v66
	v_mul_f32_e32 v130, v68, v68
	v_mul_f32_e32 v131, v70, v70
	v_fmac_f32_e32 v128, v120, v120
	v_fmac_f32_e32 v129, v122, v122
	v_fmac_f32_e32 v130, v124, v124
	v_fmac_f32_e32 v131, v126, v126
	v_fmac_f32_e32 v128, v121, v121
	v_fmac_f32_e32 v129, v123, v123
	v_fmac_f32_e32 v130, v125, v125
	v_fmac_f32_e32 v131, v127, v127
	v_fmac_f32_e32 v128, v65, v65
	v_fmac_f32_e32 v129, v67, v67
	v_fmac_f32_e32 v130, v69, v69
	v_fmac_f32_e32 v131, v71, v71
	v_add_f32_e32 v132, v128, v129
	v_add_f32_e32 v132, v132, v130
	v_add_f32_e32 v132, v132, v131
	ds_bpermute_b32 v138, v108, v132
	s_waitcnt lgkmcnt(0)
	v_add_f32_e32 v132, v132, v138
	ds_bpermute_b32 v138, v109, v132
	s_waitcnt lgkmcnt(0)
	v_add_f32_e32 v132, v132, v138
	ds_bpermute_b32 v138, v110, v132
	s_waitcnt lgkmcnt(0)
	v_add_f32_e32 v132, v132, v138
	ds_bpermute_b32 v138, v111, v132
	s_waitcnt lgkmcnt(0)
	v_add_f32_e32 v132, v132, v138
	ds_bpermute_b32 v138, v112, v132
	s_waitcnt lgkmcnt(0)
	v_add_f32_e32 v132, v132, v138
	ds_bpermute_b32 v138, v113, v132
	s_waitcnt lgkmcnt(0)
	v_add_f32_e32 v132, v132, v138
	v_fmamk_f32 v132, v132, 0x3a800000, v177
	v_mov_b32_e32 v135, 0x800000
	v_cmp_gt_f32_e32 vcc, v135, v132
	v_mul_f32_e32 v133, 0x4b800000, v132
	s_nop 1
	v_cndmask_b32_e32 v132, v132, v133, vcc
	v_rsq_f32_e32 v132, v132
	s_nop 0
	v_mul_f32_e32 v133, 0x45800000, v132
	v_cndmask_b32_e32 v134, v132, v133, vcc
	v_mul_f32_e32 v120, v72, v120
	v_mul_f32_e32 v64, v73, v64
	v_mul_f32_e32 v121, v74, v121
	v_mul_f32_e32 v65, v75, v65
	v_mul_f32_e32 v122, v76, v122
	v_mul_f32_e32 v66, v77, v66
	v_mul_f32_e32 v123, v78, v123
	v_mul_f32_e32 v67, v79, v67
	v_mul_f32_e32 v124, v80, v124
	v_mul_f32_e32 v68, v81, v68
	v_mul_f32_e32 v125, v82, v125
	v_mul_f32_e32 v69, v83, v69
	v_mul_f32_e32 v126, v84, v126
	v_mul_f32_e32 v70, v85, v70
	v_mul_f32_e32 v127, v86, v127
	v_mul_f32_e32 v71, v87, v71
	v_fmac_f32_e32 v48, v120, v134
	v_fmac_f32_e32 v49, v64, v134
	v_fmac_f32_e32 v50, v121, v134
	v_fmac_f32_e32 v51, v65, v134
	v_fmac_f32_e32 v52, v122, v134
	v_fmac_f32_e32 v53, v66, v134
	v_fmac_f32_e32 v54, v123, v134
	v_fmac_f32_e32 v55, v67, v134
	v_fmac_f32_e32 v56, v124, v134
	v_fmac_f32_e32 v57, v68, v134
	v_fmac_f32_e32 v58, v125, v134
	v_fmac_f32_e32 v59, v69, v134
	v_fmac_f32_e32 v60, v126, v134
	v_fmac_f32_e32 v61, v70, v134
	v_fmac_f32_e32 v62, v127, v134
	v_fmac_f32_e32 v63, v71, v134
	global_store_dwordx4 v116, v[48:51], s[38:39] nt
	global_store_dwordx4 v116, v[52:55], s[38:39] offset:1024 nt
	global_store_dwordx4 v116, v[56:59], s[38:39] offset:2048 nt
	global_store_dwordx4 v116, v[60:63], s[38:39] offset:3072 nt
	s_cmp_eq_u32 s42, 0
	s_cbranch_scc1 .LnrmA_skip2
	v_mul_f32_e32 v128, v49, v49
	v_mul_f32_e32 v129, v53, v53
	v_mul_f32_e32 v130, v57, v57
	v_mul_f32_e32 v131, v61, v61
	v_fmac_f32_e32 v128, v48, v48
	v_fmac_f32_e32 v129, v52, v52
	v_fmac_f32_e32 v130, v56, v56
	v_fmac_f32_e32 v131, v60, v60
	v_fmac_f32_e32 v128, v50, v50
	v_fmac_f32_e32 v129, v54, v54
	v_fmac_f32_e32 v130, v58, v58
	v_fmac_f32_e32 v131, v62, v62
	v_fmac_f32_e32 v128, v51, v51
	v_fmac_f32_e32 v129, v55, v55
	v_fmac_f32_e32 v130, v59, v59
	v_fmac_f32_e32 v131, v63, v63
	v_add_f32_e32 v132, v128, v129
	v_add_f32_e32 v132, v130, v132
	v_add_f32_e32 v132, v131, v132
	ds_bpermute_b32 v138, v108, v132
	s_waitcnt lgkmcnt(0)
	v_add_f32_e32 v132, v132, v138
	ds_bpermute_b32 v138, v109, v132
	s_waitcnt lgkmcnt(0)
	v_add_f32_e32 v132, v132, v138
	ds_bpermute_b32 v138, v110, v132
	s_waitcnt lgkmcnt(0)
	v_add_f32_e32 v132, v132, v138
	ds_bpermute_b32 v138, v111, v132
	s_waitcnt lgkmcnt(0)
	v_add_f32_e32 v132, v132, v138
	ds_bpermute_b32 v138, v112, v132
	s_waitcnt lgkmcnt(0)
	v_add_f32_e32 v132, v132, v138
	ds_bpermute_b32 v138, v113, v132
	s_waitcnt lgkmcnt(0)
	v_add_f32_e32 v132, v132, v138
	v_fmamk_f32 v132, v132, 0x3a800000, v177
	v_mov_b32_e32 v135, 0x800000
	v_cmp_gt_f32_e32 vcc, v135, v132
	v_mul_f32_e32 v133, 0x4b800000, v132
	s_nop 1
	v_cndmask_b32_e32 v132, v132, v133, vcc
	v_rsq_f32_e32 v132, v132
	s_nop 0
	v_mul_f32_e32 v133, 0x45800000, v132
	v_cndmask_b32_e32 v134, v132, v133, vcc
	v_mul_f32_e32 v48, v48, v88
	v_mul_f32_e32 v49, v49, v89
	v_mul_f32_e32 v50, v50, v90
	v_mul_f32_e32 v51, v51, v91
	v_mul_f32_e32 v52, v52, v92
	v_mul_f32_e32 v53, v53, v93
	v_mul_f32_e32 v54, v54, v94
	v_mul_f32_e32 v55, v55, v95
	v_mul_f32_e32 v56, v56, v96
	v_mul_f32_e32 v57, v57, v97
	v_mul_f32_e32 v58, v58, v98
	v_mul_f32_e32 v59, v59, v99
	v_mul_f32_e32 v60, v60, v100
	v_mul_f32_e32 v61, v61, v101
	v_mul_f32_e32 v62, v62, v102
	v_mul_f32_e32 v63, v63, v103
	v_mul_f32_e32 v48, v48, v134
	v_mul_f32_e32 v49, v49, v134
	v_mul_f32_e32 v50, v50, v134
	v_mul_f32_e32 v51, v51, v134
	v_mul_f32_e32 v52, v52, v134
	v_mul_f32_e32 v53, v53, v134
	v_mul_f32_e32 v54, v54, v134
	v_mul_f32_e32 v55, v55, v134
	v_mul_f32_e32 v56, v56, v134
	v_mul_f32_e32 v57, v57, v134
	v_mul_f32_e32 v58, v58, v134
	v_mul_f32_e32 v59, v59, v134
	v_mul_f32_e32 v60, v60, v134
	v_mul_f32_e32 v61, v61, v134
	v_mul_f32_e32 v62, v62, v134
	v_mul_f32_e32 v63, v63, v134
	v_cvt_pk_bf16_f32 v120, v48, v49
	v_cvt_pk_bf16_f32 v121, v50, v51
	v_cvt_pk_bf16_f32 v122, v52, v53
	v_cvt_pk_bf16_f32 v123, v54, v55
	v_cvt_pk_bf16_f32 v124, v56, v57
	v_cvt_pk_bf16_f32 v125, v58, v59
	v_cvt_pk_bf16_f32 v126, v60, v61
	v_cvt_pk_bf16_f32 v127, v62, v63
	global_store_dwordx2 v119, v[120:121], s[4:5] nt
	global_store_dwordx2 v119, v[122:123], s[4:5] offset:512 nt
	global_store_dwordx2 v119, v[124:125], s[4:5] offset:1024 nt
	global_store_dwordx2 v119, v[126:127], s[4:5] offset:1536 nt

.Lnrmtail_3:
	s_cmpk_lt_i32 s37, 0x4100
	s_cselect_b32 s37, s37, s36
	s_cmpk_gt_i32 s37, 0x207f
	s_cselect_b32 s43, 0x2080, 0
	s_cselect_b32 vcc_lo, 0x2000, 0
	s_cselect_b32 vcc_hi, 0x80, 0
	s_sub_i32 s43, s37, s43
	s_add_i32 vcc_lo, vcc_lo, s43
	s_addk_i32 vcc_lo, 0xff80
	s_add_i32 vcc_hi, vcc_hi, s43
	s_cmpk_lt_i32 s43, 0x80
	s_cselect_b32 vcc_lo, vcc_hi, vcc_lo
	s_cselect_b32 s38, s40, s92
	s_cselect_b32 s39, s41, s93
	s_lshl_b32 vcc_lo, vcc_lo, 12
	s_lshl_b32 vcc_hi, s37, 11
	v_add_u32_e32 v116, vcc_lo, v106
	v_add_u32_e32 v119, vcc_hi, v107
	global_load_dwordx2 v[64:65], v119, s[4:5] nt
	global_load_dwordx2 v[66:67], v119, s[4:5] offset:512 nt
	global_load_dwordx2 v[68:69], v119, s[4:5] offset:1024 nt
	global_load_dwordx2 v[70:71], v119, s[4:5] offset:1536 nt
	global_load_dwordx4 v[48:51], v116, s[38:39] nt
	global_load_dwordx4 v[52:55], v116, s[38:39] offset:1024 nt
	global_load_dwordx4 v[56:59], v116, s[38:39] offset:2048 nt
	global_load_dwordx4 v[60:63], v116, s[38:39] offset:3072 nt
	s_waitcnt vmcnt(16)
	v_lshlrev_b32_e32 v120, 16, v16
	v_and_b32_e32 v16, 0xffff0000, v16
	v_lshlrev_b32_e32 v121, 16, v17
	v_and_b32_e32 v17, 0xffff0000, v17
	v_lshlrev_b32_e32 v122, 16, v18
	v_and_b32_e32 v18, 0xffff0000, v18
	v_lshlrev_b32_e32 v123, 16, v19
	v_and_b32_e32 v19, 0xffff0000, v19
	v_lshlrev_b32_e32 v124, 16, v20
	v_and_b32_e32 v20, 0xffff0000, v20
	v_lshlrev_b32_e32 v125, 16, v21
	v_and_b32_e32 v21, 0xffff0000, v21
	v_lshlrev_b32_e32 v126, 16, v22
	v_and_b32_e32 v22, 0xffff0000, v22
	v_lshlrev_b32_e32 v127, 16, v23
	v_and_b32_e32 v23, 0xffff0000, v23
	v_mul_f32_e32 v128, v16, v16
	v_mul_f32_e32 v129, v18, v18
	v_mul_f32_e32 v130, v20, v20
	v_mul_f32_e32 v131, v22, v22
	v_fmac_f32_e32 v128, v120, v120
	v_fmac_f32_e32 v129, v122, v122
	v_fmac_f32_e32 v130, v124, v124
	v_fmac_f32_e32 v131, v126, v126
	v_fmac_f32_e32 v128, v121, v121
	v_fmac_f32_e32 v129, v123, v123
	v_fmac_f32_e32 v130, v125, v125
	v_fmac_f32_e32 v131, v127, v127
	v_fmac_f32_e32 v128, v17, v17
	v_fmac_f32_e32 v129, v19, v19
	v_fmac_f32_e32 v130, v21, v21
	v_fmac_f32_e32 v131, v23, v23
	v_add_f32_e32 v132, v128, v129
	v_add_f32_e32 v132, v132, v130
	v_add_f32_e32 v132, v132, v131
	ds_bpermute_b32 v138, v108, v132
	s_waitcnt lgkmcnt(0)
	v_add_f32_e32 v132, v132, v138
	ds_bpermute_b32 v138, v109, v132
	s_waitcnt lgkmcnt(0)
	v_add_f32_e32 v132, v132, v138
	ds_bpermute_b32 v138, v110, v132
	s_waitcnt lgkmcnt(0)
	v_add_f32_e32 v132, v132, v138
	ds_bpermute_b32 v138, v111, v132
	s_waitcnt lgkmcnt(0)
	v_add_f32_e32 v132, v132, v138
	ds_bpermute_b32 v138, v112, v132
	s_waitcnt lgkmcnt(0)
	v_add_f32_e32 v132, v132, v138
	ds_bpermute_b32 v138, v113, v132
	s_waitcnt lgkmcnt(0)
	v_add_f32_e32 v132, v132, v138
	v_fmamk_f32 v132, v132, 0x3a800000, v177
	v_mov_b32_e32 v135, 0x800000
	v_cmp_gt_f32_e32 vcc, v135, v132
	v_mul_f32_e32 v133, 0x4b800000, v132
	s_nop 1
	v_cndmask_b32_e32 v132, v132, v133, vcc
	v_rsq_f32_e32 v132, v132
	s_nop 0
	v_mul_f32_e32 v133, 0x45800000, v132
	v_cndmask_b32_e32 v132, v132, v133, vcc
	v_mul_f32_e32 v134, 0.5, v132
	v_mul_f32_e32 v120, v72, v120
	v_mul_f32_e32 v16, v73, v16
	v_mul_f32_e32 v121, v74, v121
	v_mul_f32_e32 v17, v75, v17
	v_mul_f32_e32 v122, v76, v122
	v_mul_f32_e32 v18, v77, v18
	v_mul_f32_e32 v123, v78, v123
	v_mul_f32_e32 v19, v79, v19
	v_mul_f32_e32 v124, v80, v124
	v_mul_f32_e32 v20, v81, v20
	v_mul_f32_e32 v125, v82, v125
	v_mul_f32_e32 v21, v83, v21
	v_mul_f32_e32 v126, v84, v126
	v_mul_f32_e32 v22, v85, v22
	v_mul_f32_e32 v127, v86, v127
	v_mul_f32_e32 v23, v87, v23
	v_fmac_f32_e32 v0, v120, v134
	v_fmac_f32_e32 v1, v16, v134
	v_fmac_f32_e32 v2, v121, v134
	v_fmac_f32_e32 v3, v17, v134
	v_fmac_f32_e32 v4, v122, v134
	v_fmac_f32_e32 v5, v18, v134
	v_fmac_f32_e32 v6, v123, v134
	v_fmac_f32_e32 v7, v19, v134
	v_fmac_f32_e32 v8, v124, v134
	v_fmac_f32_e32 v9, v20, v134
	v_fmac_f32_e32 v10, v125, v134
	v_fmac_f32_e32 v11, v21, v134
	v_fmac_f32_e32 v12, v126, v134
	v_fmac_f32_e32 v13, v22, v134
	v_fmac_f32_e32 v14, v127, v134
	v_fmac_f32_e32 v15, v23, v134
	global_store_dwordx4 v114, v[0:3], s[0:1] nt
	global_store_dwordx4 v114, v[4:7], s[0:1] offset:1024 nt
	global_store_dwordx4 v114, v[8:11], s[0:1] offset:2048 nt
	global_store_dwordx4 v114, v[12:15], s[0:1] offset:3072 nt
	s_cmp_eq_u32 s42, 0
	s_cbranch_scc1 .LnrmB_nopre0
	v_mul_f32_e32 v128, v1, v1
	v_mul_f32_e32 v129, v5, v5
	v_mul_f32_e32 v130, v9, v9
	v_mul_f32_e32 v131, v13, v13
	v_fmac_f32_e32 v128, v0, v0
	v_fmac_f32_e32 v129, v4, v4
	v_fmac_f32_e32 v130, v8, v8
	v_fmac_f32_e32 v131, v12, v12
	v_fmac_f32_e32 v128, v2, v2
	v_fmac_f32_e32 v129, v6, v6
	v_fmac_f32_e32 v130, v10, v10
	v_fmac_f32_e32 v131, v14, v14
	v_fmac_f32_e32 v128, v3, v3
	v_fmac_f32_e32 v129, v7, v7
	v_fmac_f32_e32 v130, v11, v11
	v_fmac_f32_e32 v131, v15, v15
	v_add_f32_e32 v132, v128, v129
	v_add_f32_e32 v132, v130, v132
	v_add_f32_e32 v132, v131, v132
	ds_bpermute_b32 v138, v108, v132
	s_waitcnt lgkmcnt(0)
	v_add_f32_e32 v132, v132, v138
	ds_bpermute_b32 v138, v109, v132
	s_waitcnt lgkmcnt(0)
	v_add_f32_e32 v132, v132, v138
	ds_bpermute_b32 v138, v110, v132
	s_waitcnt lgkmcnt(0)
	v_add_f32_e32 v132, v132, v138
	ds_bpermute_b32 v138, v111, v132
	s_waitcnt lgkmcnt(0)
	v_add_f32_e32 v132, v132, v138
	ds_bpermute_b32 v138, v112, v132
	s_waitcnt lgkmcnt(0)
	v_add_f32_e32 v132, v132, v138
	ds_bpermute_b32 v138, v113, v132
	s_waitcnt lgkmcnt(0)
	v_add_f32_e32 v132, v132, v138
	v_fmamk_f32 v132, v132, 0x3a800000, v177
	v_mov_b32_e32 v135, 0x800000
	v_cmp_gt_f32_e32 vcc, v135, v132
	v_mul_f32_e32 v133, 0x4b800000, v132
	s_nop 1
	v_cndmask_b32_e32 v132, v132, v133, vcc
	v_rsq_f32_e32 v132, v132
	s_nop 0
	v_mul_f32_e32 v133, 0x45800000, v132
	v_cndmask_b32_e32 v134, v132, v133, vcc
	v_mul_f32_e32 v0, v0, v88
	v_mul_f32_e32 v1, v1, v89
	v_mul_f32_e32 v2, v2, v90
	v_mul_f32_e32 v3, v3, v91
	v_mul_f32_e32 v4, v4, v92
	v_mul_f32_e32 v5, v5, v93
	v_mul_f32_e32 v6, v6, v94
	v_mul_f32_e32 v7, v7, v95
	v_mul_f32_e32 v8, v8, v96
	v_mul_f32_e32 v9, v9, v97
	v_mul_f32_e32 v10, v10, v98
	v_mul_f32_e32 v11, v11, v99
	v_mul_f32_e32 v12, v12, v100
	v_mul_f32_e32 v13, v13, v101
	v_mul_f32_e32 v14, v14, v102
	v_mul_f32_e32 v15, v15, v103
	v_mul_f32_e32 v0, v0, v134
	v_mul_f32_e32 v1, v1, v134
	v_mul_f32_e32 v2, v2, v134
	v_mul_f32_e32 v3, v3, v134
	v_mul_f32_e32 v4, v4, v134
	v_mul_f32_e32 v5, v5, v134
	v_mul_f32_e32 v6, v6, v134
	v_mul_f32_e32 v7, v7, v134
	v_mul_f32_e32 v8, v8, v134
	v_mul_f32_e32 v9, v9, v134
	v_mul_f32_e32 v10, v10, v134
	v_mul_f32_e32 v11, v11, v134
	v_mul_f32_e32 v12, v12, v134
	v_mul_f32_e32 v13, v13, v134
	v_mul_f32_e32 v14, v14, v134
	v_mul_f32_e32 v15, v15, v134
	v_cvt_pk_bf16_f32 v120, v0, v1
	v_cvt_pk_bf16_f32 v121, v2, v3
	v_cvt_pk_bf16_f32 v122, v4, v5
	v_cvt_pk_bf16_f32 v123, v6, v7
	v_cvt_pk_bf16_f32 v124, v8, v9
	v_cvt_pk_bf16_f32 v125, v10, v11
	v_cvt_pk_bf16_f32 v126, v12, v13
	v_cvt_pk_bf16_f32 v127, v14, v15
	global_store_dwordx2 v117, v[120:121], s[4:5] nt
	global_store_dwordx2 v117, v[122:123], s[4:5] offset:512 nt
	global_store_dwordx2 v117, v[124:125], s[4:5] offset:1024 nt
	global_store_dwordx2 v117, v[126:127], s[4:5] offset:1536 nt

.Lnrmtail_4:
	s_cmpk_lt_i32 s37, 0x4100
	s_cbranch_scc0 .LnrmB_skip2
	s_waitcnt vmcnt(8)
	v_lshlrev_b32_e32 v120, 16, v64
	v_and_b32_e32 v64, 0xffff0000, v64
	v_lshlrev_b32_e32 v121, 16, v65
	v_and_b32_e32 v65, 0xffff0000, v65
	v_lshlrev_b32_e32 v122, 16, v66
	v_and_b32_e32 v66, 0xffff0000, v66
	v_lshlrev_b32_e32 v123, 16, v67
	v_and_b32_e32 v67, 0xffff0000, v67
	v_lshlrev_b32_e32 v124, 16, v68
	v_and_b32_e32 v68, 0xffff0000, v68
	v_lshlrev_b32_e32 v125, 16, v69
	v_and_b32_e32 v69, 0xffff0000, v69
	v_lshlrev_b32_e32 v126, 16, v70
	v_and_b32_e32 v70, 0xffff0000, v70
	v_lshlrev_b32_e32 v127, 16, v71
	v_and_b32_e32 v71, 0xffff0000, v71
	v_mul_f32_e32 v128, v64, v64
	v_mul_f32_e32 v129, v66, v66
	v_mul_f32_e32 v130, v68, v68
	v_mul_f32_e32 v131, v70, v70
	v_fmac_f32_e32 v128, v120, v120
	v_fmac_f32_e32 v129, v122, v122
	v_fmac_f32_e32 v130, v124, v124
	v_fmac_f32_e32 v131, v126, v126
	v_fmac_f32_e32 v128, v121, v121
	v_fmac_f32_e32 v129, v123, v123
	v_fmac_f32_e32 v130, v125, v125
	v_fmac_f32_e32 v131, v127, v127
	v_fmac_f32_e32 v128, v65, v65
	v_fmac_f32_e32 v129, v67, v67
	v_fmac_f32_e32 v130, v69, v69
	v_fmac_f32_e32 v131, v71, v71
	v_add_f32_e32 v132, v128, v129
	v_add_f32_e32 v132, v132, v130
	v_add_f32_e32 v132, v132, v131
	ds_bpermute_b32 v138, v108, v132
	s_waitcnt lgkmcnt(0)
	v_add_f32_e32 v132, v132, v138
	ds_bpermute_b32 v138, v109, v132
	s_waitcnt lgkmcnt(0)
	v_add_f32_e32 v132, v132, v138
	ds_bpermute_b32 v138, v110, v132
	s_waitcnt lgkmcnt(0)
	v_add_f32_e32 v132, v132, v138
	ds_bpermute_b32 v138, v111, v132
	s_waitcnt lgkmcnt(0)
	v_add_f32_e32 v132, v132, v138
	ds_bpermute_b32 v138, v112, v132
	s_waitcnt lgkmcnt(0)
	v_add_f32_e32 v132, v132, v138
	ds_bpermute_b32 v138, v113, v132
	s_waitcnt lgkmcnt(0)
	v_add_f32_e32 v132, v132, v138
	v_fmamk_f32 v132, v132, 0x3a800000, v177
	v_mov_b32_e32 v135, 0x800000
	v_cmp_gt_f32_e32 vcc, v135, v132
	v_mul_f32_e32 v133, 0x4b800000, v132
	s_nop 1
	v_cndmask_b32_e32 v132, v132, v133, vcc
	v_rsq_f32_e32 v132, v132
	s_nop 0
	v_mul_f32_e32 v133, 0x45800000, v132
	v_cndmask_b32_e32 v132, v132, v133, vcc
	v_mul_f32_e32 v134, 0.5, v132
	v_mul_f32_e32 v120, v72, v120
	v_mul_f32_e32 v64, v73, v64
	v_mul_f32_e32 v121, v74, v121
	v_mul_f32_e32 v65, v75, v65
	v_mul_f32_e32 v122, v76, v122
	v_mul_f32_e32 v66, v77, v66
	v_mul_f32_e32 v123, v78, v123
	v_mul_f32_e32 v67, v79, v67
	v_mul_f32_e32 v124, v80, v124
	v_mul_f32_e32 v68, v81, v68
	v_mul_f32_e32 v125, v82, v125
	v_mul_f32_e32 v69, v83, v69
	v_mul_f32_e32 v126, v84, v126
	v_mul_f32_e32 v70, v85, v70
	v_mul_f32_e32 v127, v86, v127
	v_mul_f32_e32 v71, v87, v71
	v_fmac_f32_e32 v48, v120, v134
	v_fmac_f32_e32 v49, v64, v134
	v_fmac_f32_e32 v50, v121, v134
	v_fmac_f32_e32 v51, v65, v134
	v_fmac_f32_e32 v52, v122, v134
	v_fmac_f32_e32 v53, v66, v134
	v_fmac_f32_e32 v54, v123, v134
	v_fmac_f32_e32 v55, v67, v134
	v_fmac_f32_e32 v56, v124, v134
	v_fmac_f32_e32 v57, v68, v134
	v_fmac_f32_e32 v58, v125, v134
	v_fmac_f32_e32 v59, v69, v134
	v_fmac_f32_e32 v60, v126, v134
	v_fmac_f32_e32 v61, v70, v134
	v_fmac_f32_e32 v62, v127, v134
	v_fmac_f32_e32 v63, v71, v134
	global_store_dwordx4 v116, v[48:51], s[38:39] nt
	global_store_dwordx4 v116, v[52:55], s[38:39] offset:1024 nt
	global_store_dwordx4 v116, v[56:59], s[38:39] offset:2048 nt
	global_store_dwordx4 v116, v[60:63], s[38:39] offset:3072 nt
	s_cmp_eq_u32 s42, 0
	s_cbranch_scc1 .LnrmB_skip2
	v_mul_f32_e32 v128, v49, v49
	v_mul_f32_e32 v129, v53, v53
	v_mul_f32_e32 v130, v57, v57
	v_mul_f32_e32 v131, v61, v61
	v_fmac_f32_e32 v128, v48, v48
	v_fmac_f32_e32 v129, v52, v52
	v_fmac_f32_e32 v130, v56, v56
	v_fmac_f32_e32 v131, v60, v60
	v_fmac_f32_e32 v128, v50, v50
	v_fmac_f32_e32 v129, v54, v54
	v_fmac_f32_e32 v130, v58, v58
	v_fmac_f32_e32 v131, v62, v62
	v_fmac_f32_e32 v128, v51, v51
	v_fmac_f32_e32 v129, v55, v55
	v_fmac_f32_e32 v130, v59, v59
	v_fmac_f32_e32 v131, v63, v63
	v_add_f32_e32 v132, v128, v129
	v_add_f32_e32 v132, v130, v132
	v_add_f32_e32 v132, v131, v132
	ds_bpermute_b32 v138, v108, v132
	s_waitcnt lgkmcnt(0)
	v_add_f32_e32 v132, v132, v138
	ds_bpermute_b32 v138, v109, v132
	s_waitcnt lgkmcnt(0)
	v_add_f32_e32 v132, v132, v138
	ds_bpermute_b32 v138, v110, v132
	s_waitcnt lgkmcnt(0)
	v_add_f32_e32 v132, v132, v138
	ds_bpermute_b32 v138, v111, v132
	s_waitcnt lgkmcnt(0)
	v_add_f32_e32 v132, v132, v138
	ds_bpermute_b32 v138, v112, v132
	s_waitcnt lgkmcnt(0)
	v_add_f32_e32 v132, v132, v138
	ds_bpermute_b32 v138, v113, v132
	s_waitcnt lgkmcnt(0)
	v_add_f32_e32 v132, v132, v138
	v_fmamk_f32 v132, v132, 0x3a800000, v177
	v_mov_b32_e32 v135, 0x800000
	v_cmp_gt_f32_e32 vcc, v135, v132
	v_mul_f32_e32 v133, 0x4b800000, v132
	s_nop 1
	v_cndmask_b32_e32 v132, v132, v133, vcc
	v_rsq_f32_e32 v132, v132
	s_nop 0
	v_mul_f32_e32 v133, 0x45800000, v132
	v_cndmask_b32_e32 v134, v132, v133, vcc
	v_mul_f32_e32 v48, v48, v88
	v_mul_f32_e32 v49, v49, v89
	v_mul_f32_e32 v50, v50, v90
	v_mul_f32_e32 v51, v51, v91
	v_mul_f32_e32 v52, v52, v92
	v_mul_f32_e32 v53, v53, v93
	v_mul_f32_e32 v54, v54, v94
	v_mul_f32_e32 v55, v55, v95
	v_mul_f32_e32 v56, v56, v96
	v_mul_f32_e32 v57, v57, v97
	v_mul_f32_e32 v58, v58, v98
	v_mul_f32_e32 v59, v59, v99
	v_mul_f32_e32 v60, v60, v100
	v_mul_f32_e32 v61, v61, v101
	v_mul_f32_e32 v62, v62, v102
	v_mul_f32_e32 v63, v63, v103
	v_mul_f32_e32 v48, v48, v134
	v_mul_f32_e32 v49, v49, v134
	v_mul_f32_e32 v50, v50, v134
	v_mul_f32_e32 v51, v51, v134
	v_mul_f32_e32 v52, v52, v134
	v_mul_f32_e32 v53, v53, v134
	v_mul_f32_e32 v54, v54, v134
	v_mul_f32_e32 v55, v55, v134
	v_mul_f32_e32 v56, v56, v134
	v_mul_f32_e32 v57, v57, v134
	v_mul_f32_e32 v58, v58, v134
	v_mul_f32_e32 v59, v59, v134
	v_mul_f32_e32 v60, v60, v134
	v_mul_f32_e32 v61, v61, v134
	v_mul_f32_e32 v62, v62, v134
	v_mul_f32_e32 v63, v63, v134
	v_cvt_pk_bf16_f32 v120, v48, v49
	v_cvt_pk_bf16_f32 v121, v50, v51
	v_cvt_pk_bf16_f32 v122, v52, v53
	v_cvt_pk_bf16_f32 v123, v54, v55
	v_cvt_pk_bf16_f32 v124, v56, v57
	v_cvt_pk_bf16_f32 v125, v58, v59
	v_cvt_pk_bf16_f32 v126, v60, v61
	v_cvt_pk_bf16_f32 v127, v62, v63
	global_store_dwordx2 v119, v[120:121], s[4:5] nt
	global_store_dwordx2 v119, v[122:123], s[4:5] offset:512 nt
	global_store_dwordx2 v119, v[124:125], s[4:5] offset:1024 nt
	global_store_dwordx2 v119, v[126:127], s[4:5] offset:1536 nt

.LBB0_1765:
	s_andn2_b64 vcc, exec, s[44:45]
	s_cbranch_vccnz .LBB0_1799
	s_waitcnt vmcnt(0)
	v_lshrrev_b32_e32 v104, 6, v136
	v_and_b32_e32 v105, 63, v136
	v_readfirstlane_b32 s36, v104
	v_lshlrev_b32_e32 v106, 4, v105
	v_lshlrev_b32_e32 v107, 3, v105
	s_add_i32 s36, s82, s36
	s_cmpk_lt_i32 s36, 0x4100
	s_cbranch_scc0 .Lnrm0_done
	v_xor_b32_e32 v108, 32, v105
	v_xor_b32_e32 v109, 16, v105
	v_xor_b32_e32 v110, 8, v105
	v_xor_b32_e32 v111, 4, v105
	v_xor_b32_e32 v112, 2, v105
	v_xor_b32_e32 v113, 1, v105
	v_lshlrev_b32_e32 v108, 2, v108
	v_lshlrev_b32_e32 v109, 2, v109
	v_lshlrev_b32_e32 v110, 2, v110
	v_lshlrev_b32_e32 v111, 2, v111
	v_lshlrev_b32_e32 v112, 2, v112
	v_lshlrev_b32_e32 v113, 2, v113
	v_readlane_b32 s48, v251, 36
	v_readlane_b32 s49, v251, 37
	v_readlane_b32 s56, v251, 8
	v_readlane_b32 s57, v251, 9
	v_readlane_b32 s58, v251, 10
	v_readlane_b32 s59, v251, 11
	v_readlane_b32 s40, v252, 44
	v_readlane_b32 s41, v252, 45
	s_nop 4
	s_cmp_lg_u64 s[48:49], 0
	s_cselect_b32 s42, 1, 0
	s_cbranch_scc0 .Lnrm0_loop
	global_load_dwordx4 v[88:91], v106, s[48:49]
	global_load_dwordx4 v[92:95], v106, s[48:49] offset:1024
	global_load_dwordx4 v[96:99], v106, s[48:49] offset:2048
	global_load_dwordx4 v[100:103], v106, s[48:49] offset:3072
.Lnrm0_loop:
	s_mov_b32 s37, s36
	s_cmpk_gt_i32 s37, 0x207f
	s_cselect_b32 s43, 0x2080, 0
	s_cselect_b32 vcc_lo, 0x2000, 0
	s_cselect_b32 vcc_hi, 0x80, 0
	s_sub_i32 s43, s37, s43
	s_add_i32 vcc_lo, vcc_lo, s43
	s_addk_i32 vcc_lo, 0xff80
	s_add_i32 vcc_hi, vcc_hi, s43
	s_sub_i32 s55, s43, 0x70
	s_cmpk_lt_i32 s43, 0x70
	s_cselect_b32 s55, 0, s55
	s_cselect_b32 s52, 1, 0
	s_cmpk_lt_i32 s43, 0x80
	s_cselect_b32 s55, s55, vcc_lo
	s_cselect_b32 s44, s58, s56
	s_cselect_b32 s45, s59, s57
	s_cselect_b32 vcc_lo, vcc_hi, vcc_lo
	s_cselect_b32 s0, s40, s92
	s_cselect_b32 s1, s41, s93
	s_lshl_b32 vcc_lo, vcc_lo, 12
	s_lshl_b32 s55, s55, 12
	s_lshl_b32 vcc_hi, s37, 11
	v_add_u32_e32 v114, vcc_lo, v106
	v_add_u32_e32 v117, s55, v106
	v_add_u32_e32 v120, vcc_hi, v107
	global_load_dwordx4 v[0:3], v117, s[44:45]
	global_load_dwordx4 v[4:7], v117, s[44:45] offset:1024
	global_load_dwordx4 v[8:11], v117, s[44:45] offset:2048
	global_load_dwordx4 v[12:15], v117, s[44:45] offset:3072
	s_add_i32 s37, s36, s14
	s_cmpk_lt_i32 s37, 0x4100
	s_cselect_b32 s37, s37, s36
	s_cmpk_gt_i32 s37, 0x207f
	s_cselect_b32 s43, 0x2080, 0
	s_cselect_b32 vcc_lo, 0x2000, 0
	s_cselect_b32 vcc_hi, 0x80, 0
	s_sub_i32 s43, s37, s43
	s_add_i32 vcc_lo, vcc_lo, s43
	s_addk_i32 vcc_lo, 0xff80
	s_add_i32 vcc_hi, vcc_hi, s43
	s_sub_i32 s55, s43, 0x70
	s_cmpk_lt_i32 s43, 0x70
	s_cselect_b32 s55, 0, s55
	s_cselect_b32 s53, 1, 0
	s_cmpk_lt_i32 s43, 0x80
	s_cselect_b32 s55, s55, vcc_lo
	s_cselect_b32 s46, s58, s56
	s_cselect_b32 s47, s59, s57
	s_cselect_b32 vcc_lo, vcc_hi, vcc_lo
	s_cselect_b32 s12, s40, s92
	s_cselect_b32 s13, s41, s93
	s_lshl_b32 vcc_lo, vcc_lo, 12
	s_lshl_b32 s55, s55, 12
	s_lshl_b32 vcc_hi, s37, 11
	v_add_u32_e32 v115, vcc_lo, v106
	v_add_u32_e32 v118, s55, v106
	v_add_u32_e32 v121, vcc_hi, v107
	global_load_dwordx4 v[24:27], v118, s[46:47]
	global_load_dwordx4 v[28:31], v118, s[46:47] offset:1024
	global_load_dwordx4 v[32:35], v118, s[46:47] offset:2048
	global_load_dwordx4 v[36:39], v118, s[46:47] offset:3072
	s_lshl_b32 s37, s14, 1
	s_add_i32 s37, s36, s37
	s_cmpk_lg_i32 s14, 0x800
	s_cbranch_scc1 .Lnrmtail_7
	s_cmpk_lt_i32 s37, 0x4000
	s_cbranch_scc1 .Lnrmtail_7
	s_sub_i32 vcc_lo, s36, s82
	s_and_b32 vcc_lo, vcc_lo, 7
	s_add_i32 s37, s2, 0x4000
	s_cmp_eq_u32 vcc_lo, 0
	s_cselect_b32 s37, s37, 0x7fff
.Lnrmtail_7:
	s_cmpk_lt_i32 s37, 0x4100
	s_cselect_b32 s37, s37, s36
	s_cmpk_gt_i32 s37, 0x207f
	s_cselect_b32 s43, 0x2080, 0
	s_cselect_b32 vcc_lo, 0x2000, 0
	s_cselect_b32 vcc_hi, 0x80, 0
	s_sub_i32 s43, s37, s43
	s_add_i32 vcc_lo, vcc_lo, s43
	s_addk_i32 vcc_lo, 0xff80
	s_add_i32 vcc_hi, vcc_hi, s43
	s_sub_i32 s55, s43, 0x70
	s_cmpk_lt_i32 s43, 0x70
	s_cselect_b32 s55, 0, s55
	s_cselect_b32 s54, 1, 0
	s_cmpk_lt_i32 s43, 0x80
	s_cselect_b32 s55, s55, vcc_lo
	s_cselect_b32 s50, s58, s56
	s_cselect_b32 s51, s59, s57
	s_cselect_b32 vcc_lo, vcc_hi, vcc_lo
	s_cselect_b32 s38, s40, s92
	s_cselect_b32 s39, s41, s93
	s_lshl_b32 vcc_lo, vcc_lo, 12
	s_lshl_b32 s55, s55, 12
	s_lshl_b32 vcc_hi, s37, 11
	v_add_u32_e32 v116, vcc_lo, v106
	v_add_u32_e32 v119, s55, v106
	v_add_u32_e32 v122, vcc_hi, v107
	global_load_dwordx4 v[48:51], v119, s[50:51]
	global_load_dwordx4 v[52:55], v119, s[50:51] offset:1024
	global_load_dwordx4 v[56:59], v119, s[50:51] offset:2048
	global_load_dwordx4 v[60:63], v119, s[50:51] offset:3072
	s_waitcnt vmcnt(8)
	s_cmp_eq_u32 s52, 0
	s_cbranch_scc1 .Lnrm0_nopad0
	v_mov_b32_e32 v0, 0
	v_mov_b32_e32 v1, 0
	v_mov_b32_e32 v2, 0
	v_mov_b32_e32 v3, 0
	v_mov_b32_e32 v4, 0
	v_mov_b32_e32 v5, 0
	v_mov_b32_e32 v6, 0
	v_mov_b32_e32 v7, 0
	v_mov_b32_e32 v8, 0
	v_mov_b32_e32 v9, 0
	v_mov_b32_e32 v10, 0
	v_mov_b32_e32 v11, 0
	v_mov_b32_e32 v12, 0
	v_mov_b32_e32 v13, 0
	v_mov_b32_e32 v14, 0
	v_mov_b32_e32 v15, 0
.Lnrm0_nopad0:
	global_store_dwordx4 v114, v[0:3], s[0:1] nt
	global_store_dwordx4 v114, v[4:7], s[0:1] offset:1024 nt
	global_store_dwordx4 v114, v[8:11], s[0:1] offset:2048 nt
	global_store_dwordx4 v114, v[12:15], s[0:1] offset:3072 nt
	s_cmp_eq_u32 s42, 0
	s_cbranch_scc1 .Lnrm0_nopre0
	v_mul_f32_e32 v132, v1, v1
	v_mul_f32_e32 v133, v5, v5
	v_mul_f32_e32 v134, v9, v9
	v_mul_f32_e32 v135, v13, v13
	v_fmac_f32_e32 v132, v0, v0
	v_fmac_f32_e32 v133, v4, v4
	v_fmac_f32_e32 v134, v8, v8
	v_fmac_f32_e32 v135, v12, v12
	v_fmac_f32_e32 v132, v2, v2
	v_fmac_f32_e32 v133, v6, v6
	v_fmac_f32_e32 v134, v10, v10
	v_fmac_f32_e32 v135, v14, v14
	v_fmac_f32_e32 v132, v3, v3
	v_fmac_f32_e32 v133, v7, v7
	v_fmac_f32_e32 v134, v11, v11
	v_fmac_f32_e32 v135, v15, v15
	v_add_f32_e32 v72, v132, v133
	v_add_f32_e32 v72, v72, v134
	v_add_f32_e32 v72, v72, v135
	ds_bpermute_b32 v138, v108, v72
	s_waitcnt lgkmcnt(0)
	v_add_f32_e32 v72, v72, v138
	ds_bpermute_b32 v138, v109, v72
	s_waitcnt lgkmcnt(0)
	v_add_f32_e32 v72, v72, v138
	ds_bpermute_b32 v138, v110, v72
	s_waitcnt lgkmcnt(0)
	v_add_f32_e32 v72, v72, v138
	ds_bpermute_b32 v138, v111, v72
	s_waitcnt lgkmcnt(0)
	v_add_f32_e32 v72, v72, v138
	ds_bpermute_b32 v138, v112, v72
	s_waitcnt lgkmcnt(0)
	v_add_f32_e32 v72, v72, v138
	ds_bpermute_b32 v138, v113, v72
	s_waitcnt lgkmcnt(0)
	v_add_f32_e32 v72, v72, v138
	v_fmamk_f32 v72, v72, 0x3a800000, v177
	v_mov_b32_e32 v75, 0x800000
	v_cmp_gt_f32_e32 vcc, v75, v72
	v_mul_f32_e32 v73, 0x4b800000, v72
	s_nop 1
	v_cndmask_b32_e32 v72, v72, v73, vcc
	v_rsq_f32_e32 v72, v72
	s_nop 0
	v_mul_f32_e32 v73, 0x45800000, v72
	v_cndmask_b32_e32 v74, v72, v73, vcc
	v_mul_f32_e32 v0, v0, v88
	v_mul_f32_e32 v1, v1, v89
	v_mul_f32_e32 v2, v2, v90
	v_mul_f32_e32 v3, v3, v91
	v_mul_f32_e32 v4, v4, v92
	v_mul_f32_e32 v5, v5, v93
	v_mul_f32_e32 v6, v6, v94
	v_mul_f32_e32 v7, v7, v95
	v_mul_f32_e32 v8, v8, v96
	v_mul_f32_e32 v9, v9, v97
	v_mul_f32_e32 v10, v10, v98
	v_mul_f32_e32 v11, v11, v99
	v_mul_f32_e32 v12, v12, v100
	v_mul_f32_e32 v13, v13, v101
	v_mul_f32_e32 v14, v14, v102
	v_mul_f32_e32 v15, v15, v103
	v_mul_f32_e32 v0, v0, v74
	v_mul_f32_e32 v1, v1, v74
	v_mul_f32_e32 v2, v2, v74
	v_mul_f32_e32 v3, v3, v74
	v_mul_f32_e32 v4, v4, v74
	v_mul_f32_e32 v5, v5, v74
	v_mul_f32_e32 v6, v6, v74
	v_mul_f32_e32 v7, v7, v74
	v_mul_f32_e32 v8, v8, v74
	v_mul_f32_e32 v9, v9, v74
	v_mul_f32_e32 v10, v10, v74
	v_mul_f32_e32 v11, v11, v74
	v_mul_f32_e32 v12, v12, v74
	v_mul_f32_e32 v13, v13, v74
	v_mul_f32_e32 v14, v14, v74
	v_mul_f32_e32 v15, v15, v74
	v_cvt_pk_bf16_f32 v124, v0, v1
	v_cvt_pk_bf16_f32 v125, v2, v3
	v_cvt_pk_bf16_f32 v126, v4, v5
	v_cvt_pk_bf16_f32 v127, v6, v7
	v_cvt_pk_bf16_f32 v128, v8, v9
	v_cvt_pk_bf16_f32 v129, v10, v11
	v_cvt_pk_bf16_f32 v130, v12, v13
	v_cvt_pk_bf16_f32 v131, v14, v15
	global_store_dwordx2 v120, v[124:125], s[4:5] nt
	global_store_dwordx2 v120, v[126:127], s[4:5] offset:512 nt
	global_store_dwordx2 v120, v[128:129], s[4:5] offset:1024 nt
	global_store_dwordx2 v120, v[130:131], s[4:5] offset:1536 nt
.Lnrm0_nopre0:
	s_add_i32 s37, s36, s14
	s_cmpk_lt_i32 s37, 0x4100
	s_cbranch_scc0 .Lnrm0_skip1
	s_waitcnt vmcnt(8)
	s_cmp_eq_u32 s53, 0
	s_cbranch_scc1 .Lnrm0_nopad1
	v_mov_b32_e32 v24, 0
	v_mov_b32_e32 v25, 0
	v_mov_b32_e32 v26, 0
	v_mov_b32_e32 v27, 0
	v_mov_b32_e32 v28, 0
	v_mov_b32_e32 v29, 0
	v_mov_b32_e32 v30, 0
	v_mov_b32_e32 v31, 0
	v_mov_b32_e32 v32, 0
	v_mov_b32_e32 v33, 0
	v_mov_b32_e32 v34, 0
	v_mov_b32_e32 v35, 0
	v_mov_b32_e32 v36, 0
	v_mov_b32_e32 v37, 0
	v_mov_b32_e32 v38, 0
	v_mov_b32_e32 v39, 0
.Lnrm0_nopad1:
	global_store_dwordx4 v115, v[24:27], s[12:13] nt
	global_store_dwordx4 v115, v[28:31], s[12:13] offset:1024 nt
	global_store_dwordx4 v115, v[32:35], s[12:13] offset:2048 nt
	global_store_dwordx4 v115, v[36:39], s[12:13] offset:3072 nt
	s_cmp_eq_u32 s42, 0
	s_cbranch_scc1 .Lnrm0_skip1
	v_mul_f32_e32 v132, v25, v25
	v_mul_f32_e32 v133, v29, v29
	v_mul_f32_e32 v134, v33, v33
	v_mul_f32_e32 v135, v37, v37
	v_fmac_f32_e32 v132, v24, v24
	v_fmac_f32_e32 v133, v28, v28
	v_fmac_f32_e32 v134, v32, v32
	v_fmac_f32_e32 v135, v36, v36
	v_fmac_f32_e32 v132, v26, v26
	v_fmac_f32_e32 v133, v30, v30
	v_fmac_f32_e32 v134, v34, v34
	v_fmac_f32_e32 v135, v38, v38
	v_fmac_f32_e32 v132, v27, v27
	v_fmac_f32_e32 v133, v31, v31
	v_fmac_f32_e32 v134, v35, v35
	v_fmac_f32_e32 v135, v39, v39
	v_add_f32_e32 v72, v132, v133
	v_add_f32_e32 v72, v72, v134
	v_add_f32_e32 v72, v72, v135
	ds_bpermute_b32 v138, v108, v72
	s_waitcnt lgkmcnt(0)
	v_add_f32_e32 v72, v72, v138
	ds_bpermute_b32 v138, v109, v72
	s_waitcnt lgkmcnt(0)
	v_add_f32_e32 v72, v72, v138
	ds_bpermute_b32 v138, v110, v72
	s_waitcnt lgkmcnt(0)
	v_add_f32_e32 v72, v72, v138
	ds_bpermute_b32 v138, v111, v72
	s_waitcnt lgkmcnt(0)
	v_add_f32_e32 v72, v72, v138
	ds_bpermute_b32 v138, v112, v72
	s_waitcnt lgkmcnt(0)
	v_add_f32_e32 v72, v72, v138
	ds_bpermute_b32 v138, v113, v72
	s_waitcnt lgkmcnt(0)
	v_add_f32_e32 v72, v72, v138
	v_fmamk_f32 v72, v72, 0x3a800000, v177
	v_mov_b32_e32 v75, 0x800000
	v_cmp_gt_f32_e32 vcc, v75, v72
	v_mul_f32_e32 v73, 0x4b800000, v72
	s_nop 1
	v_cndmask_b32_e32 v72, v72, v73, vcc
	v_rsq_f32_e32 v72, v72
	s_nop 0
	v_mul_f32_e32 v73, 0x45800000, v72
	v_cndmask_b32_e32 v74, v72, v73, vcc
	v_mul_f32_e32 v24, v24, v88
	v_mul_f32_e32 v25, v25, v89
	v_mul_f32_e32 v26, v26, v90
	v_mul_f32_e32 v27, v27, v91
	v_mul_f32_e32 v28, v28, v92
	v_mul_f32_e32 v29, v29, v93
	v_mul_f32_e32 v30, v30, v94
	v_mul_f32_e32 v31, v31, v95
	v_mul_f32_e32 v32, v32, v96
	v_mul_f32_e32 v33, v33, v97
	v_mul_f32_e32 v34, v34, v98
	v_mul_f32_e32 v35, v35, v99
	v_mul_f32_e32 v36, v36, v100
	v_mul_f32_e32 v37, v37, v101
	v_mul_f32_e32 v38, v38, v102
	v_mul_f32_e32 v39, v39, v103
	v_mul_f32_e32 v24, v24, v74
	v_mul_f32_e32 v25, v25, v74
	v_mul_f32_e32 v26, v26, v74
	v_mul_f32_e32 v27, v27, v74
	v_mul_f32_e32 v28, v28, v74
	v_mul_f32_e32 v29, v29, v74
	v_mul_f32_e32 v30, v30, v74
	v_mul_f32_e32 v31, v31, v74
	v_mul_f32_e32 v32, v32, v74
	v_mul_f32_e32 v33, v33, v74
	v_mul_f32_e32 v34, v34, v74
	v_mul_f32_e32 v35, v35, v74
	v_mul_f32_e32 v36, v36, v74
	v_mul_f32_e32 v37, v37, v74
	v_mul_f32_e32 v38, v38, v74
	v_mul_f32_e32 v39, v39, v74
	v_cvt_pk_bf16_f32 v124, v24, v25
	v_cvt_pk_bf16_f32 v125, v26, v27
	v_cvt_pk_bf16_f32 v126, v28, v29
	v_cvt_pk_bf16_f32 v127, v30, v31
	v_cvt_pk_bf16_f32 v128, v32, v33
	v_cvt_pk_bf16_f32 v129, v34, v35
	v_cvt_pk_bf16_f32 v130, v36, v37
	v_cvt_pk_bf16_f32 v131, v38, v39
	global_store_dwordx2 v121, v[124:125], s[4:5] nt
	global_store_dwordx2 v121, v[126:127], s[4:5] offset:512 nt
	global_store_dwordx2 v121, v[128:129], s[4:5] offset:1024 nt
	global_store_dwordx2 v121, v[130:131], s[4:5] offset:1536 nt

.Lnrmtail_8:
	s_cmpk_lt_i32 s37, 0x4100
	s_cbranch_scc0 .Lnrm0_skip2
	s_waitcnt vmcnt(8)
	s_cmp_eq_u32 s54, 0
	s_cbranch_scc1 .Lnrm0_nopad2
	v_mov_b32_e32 v48, 0
	v_mov_b32_e32 v49, 0
	v_mov_b32_e32 v50, 0
	v_mov_b32_e32 v51, 0
	v_mov_b32_e32 v52, 0
	v_mov_b32_e32 v53, 0
	v_mov_b32_e32 v54, 0
	v_mov_b32_e32 v55, 0
	v_mov_b32_e32 v56, 0
	v_mov_b32_e32 v57, 0
	v_mov_b32_e32 v58, 0
	v_mov_b32_e32 v59, 0
	v_mov_b32_e32 v60, 0
	v_mov_b32_e32 v61, 0
	v_mov_b32_e32 v62, 0
	v_mov_b32_e32 v63, 0
.Lnrm0_nopad2:
	global_store_dwordx4 v116, v[48:51], s[38:39] nt
	global_store_dwordx4 v116, v[52:55], s[38:39] offset:1024 nt
	global_store_dwordx4 v116, v[56:59], s[38:39] offset:2048 nt
	global_store_dwordx4 v116, v[60:63], s[38:39] offset:3072 nt
	s_cmp_eq_u32 s42, 0
	s_cbranch_scc1 .Lnrm0_skip2
	v_mul_f32_e32 v132, v49, v49
	v_mul_f32_e32 v133, v53, v53
	v_mul_f32_e32 v134, v57, v57
	v_mul_f32_e32 v135, v61, v61
	v_fmac_f32_e32 v132, v48, v48
	v_fmac_f32_e32 v133, v52, v52
	v_fmac_f32_e32 v134, v56, v56
	v_fmac_f32_e32 v135, v60, v60
	v_fmac_f32_e32 v132, v50, v50
	v_fmac_f32_e32 v133, v54, v54
	v_fmac_f32_e32 v134, v58, v58
	v_fmac_f32_e32 v135, v62, v62
	v_fmac_f32_e32 v132, v51, v51
	v_fmac_f32_e32 v133, v55, v55
	v_fmac_f32_e32 v134, v59, v59
	v_fmac_f32_e32 v135, v63, v63
	v_add_f32_e32 v72, v132, v133
	v_add_f32_e32 v72, v72, v134
	v_add_f32_e32 v72, v72, v135
	ds_bpermute_b32 v138, v108, v72
	s_waitcnt lgkmcnt(0)
	v_add_f32_e32 v72, v72, v138
	ds_bpermute_b32 v138, v109, v72
	s_waitcnt lgkmcnt(0)
	v_add_f32_e32 v72, v72, v138
	ds_bpermute_b32 v138, v110, v72
	s_waitcnt lgkmcnt(0)
	v_add_f32_e32 v72, v72, v138
	ds_bpermute_b32 v138, v111, v72
	s_waitcnt lgkmcnt(0)
	v_add_f32_e32 v72, v72, v138
	ds_bpermute_b32 v138, v112, v72
	s_waitcnt lgkmcnt(0)
	v_add_f32_e32 v72, v72, v138
	ds_bpermute_b32 v138, v113, v72
	s_waitcnt lgkmcnt(0)
	v_add_f32_e32 v72, v72, v138
	v_fmamk_f32 v72, v72, 0x3a800000, v177
	v_mov_b32_e32 v75, 0x800000
	v_cmp_gt_f32_e32 vcc, v75, v72
	v_mul_f32_e32 v73, 0x4b800000, v72
	s_nop 1
	v_cndmask_b32_e32 v72, v72, v73, vcc
	v_rsq_f32_e32 v72, v72
	s_nop 0
	v_mul_f32_e32 v73, 0x45800000, v72
	v_cndmask_b32_e32 v74, v72, v73, vcc
	v_mul_f32_e32 v48, v48, v88
	v_mul_f32_e32 v49, v49, v89
	v_mul_f32_e32 v50, v50, v90
	v_mul_f32_e32 v51, v51, v91
	v_mul_f32_e32 v52, v52, v92
	v_mul_f32_e32 v53, v53, v93
	v_mul_f32_e32 v54, v54, v94
	v_mul_f32_e32 v55, v55, v95
	v_mul_f32_e32 v56, v56, v96
	v_mul_f32_e32 v57, v57, v97
	v_mul_f32_e32 v58, v58, v98
	v_mul_f32_e32 v59, v59, v99
	v_mul_f32_e32 v60, v60, v100
	v_mul_f32_e32 v61, v61, v101
	v_mul_f32_e32 v62, v62, v102
	v_mul_f32_e32 v63, v63, v103
	v_mul_f32_e32 v48, v48, v74
	v_mul_f32_e32 v49, v49, v74
	v_mul_f32_e32 v50, v50, v74
	v_mul_f32_e32 v51, v51, v74
	v_mul_f32_e32 v52, v52, v74
	v_mul_f32_e32 v53, v53, v74
	v_mul_f32_e32 v54, v54, v74
	v_mul_f32_e32 v55, v55, v74
	v_mul_f32_e32 v56, v56, v74
	v_mul_f32_e32 v57, v57, v74
	v_mul_f32_e32 v58, v58, v74
	v_mul_f32_e32 v59, v59, v74
	v_mul_f32_e32 v60, v60, v74
	v_mul_f32_e32 v61, v61, v74
	v_mul_f32_e32 v62, v62, v74
	v_mul_f32_e32 v63, v63, v74
	v_cvt_pk_bf16_f32 v124, v48, v49
	v_cvt_pk_bf16_f32 v125, v50, v51
	v_cvt_pk_bf16_f32 v126, v52, v53
	v_cvt_pk_bf16_f32 v127, v54, v55
	v_cvt_pk_bf16_f32 v128, v56, v57
	v_cvt_pk_bf16_f32 v129, v58, v59
	v_cvt_pk_bf16_f32 v130, v60, v61
	v_cvt_pk_bf16_f32 v131, v62, v63
	global_store_dwordx2 v122, v[124:125], s[4:5] nt
	global_store_dwordx2 v122, v[126:127], s[4:5] offset:512 nt
	global_store_dwordx2 v122, v[128:129], s[4:5] offset:1024 nt
	global_store_dwordx2 v122, v[130:131], s[4:5] offset:1536 nt

.Lnrm0_done:
.LBB0_1799:
	v_readlane_b32 s0, v249, 49
	v_readlane_b32 s1, v249, 50
	s_andn2_b64 vcc, exec, s[0:1]
	s_cbranch_vccz .LBB0_1800
	s_getpc_b64 s[98:99]
